# P0 silu(cond) fill loop unrolled: 18 loads in flight with counted vmcnt instead of load-wait per iteration
# speedup vs baseline: 1.0052x; 1.0052x over previous
; __device__ __forceinline__ void p0_ada_item(LAS unsigned char* lds, const Params& P, int item) {
;     ...
;     const int nn = tid & 15, kg = tid >> 4, n = item * 16 + nn;
;     float w[32];
; #pragma unroll
;     for (int it = 0; it < 32; ++it) w[it] = P.ada_w[(size_t)(kg + 32 * it) * 3072 + n];
;     for (int i = tid; i < 9 * 1024; i += NTHREADS) { const int r = i >> 10, k = i & 1023; const float v = r < 8 ? P.c[r * 1024 + k] : P.c_ctx[k]; S[i] = v / (1.0f + __expf(-v)); }
.LBB0_22:
	v_mov_b32_e32 v2, v167
	s_lshl_b32 s20, s28, 4
	v_and_b32_e32 v7, 15, v2
	v_or_b32_e32 v4, s20, v7
	v_ashrrev_i32_e32 v9, 4, v2
	v_ashrrev_i32_e32 v5, 31, v4
	v_lshl_add_u64 v[10:11], v[4:5], 2, s[44:45]
	v_add_u32_e32 v0, 32, v9
	v_mad_i64_i32 v[12:13], s[30:31], v0, s3, v[10:11]
	v_add_u32_e32 v0, 64, v9
	v_mad_i64_i32 v[14:15], s[30:31], v0, s3, v[10:11]
	v_add_u32_e32 v0, 0x60, v9
	v_mad_i64_i32 v[16:17], s[30:31], v0, s3, v[10:11]
	v_add_u32_e32 v0, 0x80, v9
	v_mad_i64_i32 v[18:19], s[30:31], v0, s3, v[10:11]
	v_add_u32_e32 v0, 0xa0, v9
	v_mad_i64_i32 v[20:21], s[30:31], v0, s3, v[10:11]
	v_add_u32_e32 v0, 0xc0, v9
	v_mad_i64_i32 v[22:23], s[30:31], v0, s3, v[10:11]
	v_add_u32_e32 v0, 0xe0, v9
	v_mad_i64_i32 v[24:25], s[30:31], v0, s3, v[10:11]
	v_add_u32_e32 v0, 0x100, v9
	v_mad_i64_i32 v[26:27], s[30:31], v0, s3, v[10:11]
	v_add_u32_e32 v0, 0x120, v9
	v_mad_i64_i32 v[28:29], s[30:31], v0, s3, v[10:11]
	v_add_u32_e32 v0, 0x140, v9
	v_mad_i64_i32 v[30:31], s[30:31], v0, s3, v[10:11]
	v_add_u32_e32 v0, 0x160, v9
	v_mad_i64_i32 v[32:33], s[30:31], v0, s3, v[10:11]
	v_add_u32_e32 v0, 0x180, v9
	v_mad_i64_i32 v[34:35], s[30:31], v0, s3, v[10:11]
	v_add_u32_e32 v0, 0x1a0, v9
	v_mad_i64_i32 v[36:37], s[30:31], v0, s3, v[10:11]
	v_add_u32_e32 v0, 0x1c0, v9
	v_mad_i64_i32 v[38:39], s[30:31], v0, s3, v[10:11]
	v_add_u32_e32 v0, 0x1e0, v9
	v_mad_i64_i32 v[70:71], s[30:31], v0, s3, v[10:11]
	v_add_u32_e32 v0, 0x200, v9
	v_mad_i64_i32 v[72:73], s[30:31], v0, s3, v[10:11]
	v_add_u32_e32 v0, 0x220, v9
	v_mad_i64_i32 v[74:75], s[30:31], v0, s3, v[10:11]
	v_add_u32_e32 v0, 0x240, v9
	v_mad_i64_i32 v[76:77], s[30:31], v0, s3, v[10:11]
	v_add_u32_e32 v0, 0x260, v9
	v_mad_i64_i32 v[78:79], s[30:31], v0, s3, v[10:11]
	v_add_u32_e32 v0, 0x280, v9
	v_mad_i64_i32 v[80:81], s[30:31], v0, s3, v[10:11]
	v_add_u32_e32 v0, 0x2a0, v9
	v_mad_i64_i32 v[82:83], s[30:31], v0, s3, v[10:11]
	v_add_u32_e32 v0, 0x2c0, v9
	v_mad_i64_i32 v[84:85], s[30:31], v0, s3, v[10:11]
	v_add_u32_e32 v0, 0x2e0, v9
	v_mad_i64_i32 v[86:87], s[30:31], v0, s3, v[10:11]
	v_add_u32_e32 v0, 0x300, v9
	v_mad_i64_i32 v[88:89], s[30:31], v0, s3, v[10:11]
	v_add_u32_e32 v0, 0x320, v9
	v_mad_i64_i32 v[90:91], s[30:31], v0, s3, v[10:11]
	v_add_u32_e32 v0, 0x340, v9
	v_mad_i64_i32 v[92:93], s[30:31], v0, s3, v[10:11]
	v_add_u32_e32 v0, 0x360, v9
	v_mad_i64_i32 v[94:95], s[30:31], v0, s3, v[10:11]
	v_add_u32_e32 v0, 0x380, v9
	v_mad_i64_i32 v[96:97], s[30:31], v0, s3, v[10:11]
	v_add_u32_e32 v0, 0x3a0, v9
	v_mad_i64_i32 v[98:99], s[30:31], v0, s3, v[10:11]
	v_add_u32_e32 v0, 0x3c0, v9
	v_mad_i64_i32 v[100:101], s[30:31], v0, s3, v[10:11]
	v_add_u32_e32 v0, 0x3e0, v9
	v_mad_i64_i32 v[102:103], s[30:31], v0, s3, v[10:11]
	v_mad_i64_i32 v[10:11], s[30:31], v9, s3, v[10:11]
	global_load_dword v68, v[10:11], off
	global_load_dword v66, v[12:13], off
	global_load_dword v64, v[14:15], off
	global_load_dword v62, v[16:17], off
	global_load_dword v60, v[18:19], off
	global_load_dword v58, v[20:21], off
	global_load_dword v56, v[22:23], off
	global_load_dword v54, v[24:25], off
	global_load_dword v52, v[26:27], off
	global_load_dword v50, v[28:29], off
	global_load_dword v48, v[30:31], off
	global_load_dword v46, v[32:33], off
	global_load_dword v44, v[34:35], off
	global_load_dword v42, v[36:37], off
	global_load_dword v40, v[38:39], off
	s_nop 0
	global_load_dword v38, v[70:71], off
	global_load_dword v36, v[72:73], off
	global_load_dword v34, v[74:75], off
	global_load_dword v32, v[76:77], off
	global_load_dword v30, v[78:79], off
	global_load_dword v28, v[80:81], off
	global_load_dword v26, v[82:83], off
	global_load_dword v24, v[84:85], off
	global_load_dword v22, v[86:87], off
	global_load_dword v20, v[88:89], off
	global_load_dword v18, v[90:91], off
	global_load_dword v16, v[92:93], off
	global_load_dword v14, v[94:95], off
	global_load_dword v12, v[96:97], off
	global_load_dword v10, v[98:99], off
	global_load_dword v8, v[100:101], off
	global_load_dword v6, v[102:103], off
	v_cmp_gt_i32_e32 vcc, s6, v2
	s_and_saveexec_b64 s[52:53], vcc
	s_cbranch_execz .LBB0_25
	v_lshl_add_u32 v11, v2, 2, 0
	global_load_dword v70, v11, s[38:39]
	global_load_dword v71, v11, s[38:39] offset:2048
	v_add_u32_e32 v0, 0x1000, v11
	global_load_dword v72, v0, s[38:39]
	global_load_dword v73, v0, s[38:39] offset:2048
	v_add_u32_e32 v0, 0x2000, v11
	global_load_dword v74, v0, s[38:39]
	global_load_dword v75, v0, s[38:39] offset:2048
	v_add_u32_e32 v0, 0x3000, v11
	global_load_dword v76, v0, s[38:39]
	global_load_dword v77, v0, s[38:39] offset:2048
	v_add_u32_e32 v0, 0x4000, v11
	global_load_dword v78, v0, s[38:39]
	global_load_dword v79, v0, s[38:39] offset:2048
	v_add_u32_e32 v0, 0x5000, v11
	global_load_dword v80, v0, s[38:39]
	global_load_dword v81, v0, s[38:39] offset:2048
	v_add_u32_e32 v0, 0x6000, v11
	global_load_dword v82, v0, s[38:39]
	global_load_dword v83, v0, s[38:39] offset:2048
	v_add_u32_e32 v0, 0x7000, v11
	global_load_dword v84, v0, s[38:39]
	global_load_dword v85, v0, s[38:39] offset:2048
	global_load_dword v86, v11, s[42:43]
	global_load_dword v87, v11, s[42:43] offset:2048
	s_waitcnt vmcnt(17)
	v_mul_f32_e32 v13, 0xbfb8aa3b, v70
	v_exp_f32_e32 v13, v13
	s_nop 0
	v_add_f32_e32 v13, 1.0, v13
	v_div_scale_f32 v15, s[30:31], v13, v13, v70
	v_rcp_f32_e32 v17, v15
	v_div_scale_f32 v19, vcc, v70, v13, v70
	v_fma_f32 v21, -v15, v17, 1.0
	v_fmac_f32_e32 v17, v21, v17
	v_mul_f32_e32 v21, v19, v17
	v_fma_f32 v23, -v15, v21, v19
	v_fmac_f32_e32 v21, v23, v17
	v_fma_f32 v15, -v15, v21, v19
	v_div_fmas_f32 v15, v15, v17, v21
	v_div_fixup_f32 v0, v15, v13, v70
	ds_write_b32 v11, v0
	s_waitcnt vmcnt(16)
; __device__ __forceinline__ void p0_ada_item(LAS unsigned char* lds, const Params& P, int item) {
;     ...
;     for (int i = tid; i < 9 * 1024; i += NTHREADS) { const int r = i >> 10, k = i & 1023; const float v = r < 8 ? P.c[r * 1024 + k] : P.c_ctx[k]; S[i] = v / (1.0f + __expf(-v)); }
	v_mul_f32_e32 v13, 0xbfb8aa3b, v71
	v_exp_f32_e32 v13, v13
	s_nop 0
	v_add_f32_e32 v13, 1.0, v13
	v_div_scale_f32 v15, s[30:31], v13, v13, v71
	v_rcp_f32_e32 v17, v15
	v_div_scale_f32 v19, vcc, v71, v13, v71
	v_fma_f32 v21, -v15, v17, 1.0
	v_fmac_f32_e32 v17, v21, v17
	v_mul_f32_e32 v21, v19, v17
	v_fma_f32 v23, -v15, v21, v19
	v_fmac_f32_e32 v21, v23, v17
	v_fma_f32 v15, -v15, v21, v19
	v_div_fmas_f32 v15, v15, v17, v21
	v_div_fixup_f32 v3, v15, v13, v71
	ds_write_b32 v11, v3 offset:2048
	s_waitcnt vmcnt(15)
	v_mul_f32_e32 v13, 0xbfb8aa3b, v72
	v_exp_f32_e32 v13, v13
	s_nop 0
	v_add_f32_e32 v13, 1.0, v13
	v_div_scale_f32 v15, s[30:31], v13, v13, v72
	v_rcp_f32_e32 v17, v15
	v_div_scale_f32 v19, vcc, v72, v13, v72
	v_fma_f32 v21, -v15, v17, 1.0
	v_fmac_f32_e32 v17, v21, v17
	v_mul_f32_e32 v21, v19, v17
	v_fma_f32 v23, -v15, v21, v19
	v_fmac_f32_e32 v21, v23, v17
	v_fma_f32 v15, -v15, v21, v19
	v_div_fmas_f32 v15, v15, v17, v21
	v_div_fixup_f32 v0, v15, v13, v72
	ds_write_b32 v11, v0 offset:4096
	s_waitcnt vmcnt(14)
	v_mul_f32_e32 v13, 0xbfb8aa3b, v73
	v_exp_f32_e32 v13, v13
	s_nop 0
	v_add_f32_e32 v13, 1.0, v13
	v_div_scale_f32 v15, s[30:31], v13, v13, v73
	v_rcp_f32_e32 v17, v15
	v_div_scale_f32 v19, vcc, v73, v13, v73
	v_fma_f32 v21, -v15, v17, 1.0
	v_fmac_f32_e32 v17, v21, v17
	v_mul_f32_e32 v21, v19, v17
	v_fma_f32 v23, -v15, v21, v19
	v_fmac_f32_e32 v21, v23, v17
	v_fma_f32 v15, -v15, v21, v19
	v_div_fmas_f32 v15, v15, v17, v21
	v_div_fixup_f32 v3, v15, v13, v73
	ds_write_b32 v11, v3 offset:6144
	s_waitcnt vmcnt(13)
	v_mul_f32_e32 v13, 0xbfb8aa3b, v74
	v_exp_f32_e32 v13, v13
	s_nop 0
	v_add_f32_e32 v13, 1.0, v13
	v_div_scale_f32 v15, s[30:31], v13, v13, v74
	v_rcp_f32_e32 v17, v15
	v_div_scale_f32 v19, vcc, v74, v13, v74
	v_fma_f32 v21, -v15, v17, 1.0
	v_fmac_f32_e32 v17, v21, v17
	v_mul_f32_e32 v21, v19, v17
	v_fma_f32 v23, -v15, v21, v19
	v_fmac_f32_e32 v21, v23, v17
	v_fma_f32 v15, -v15, v21, v19
	v_div_fmas_f32 v15, v15, v17, v21
	v_div_fixup_f32 v0, v15, v13, v74
	ds_write_b32 v11, v0 offset:8192
	s_waitcnt vmcnt(12)
	v_mul_f32_e32 v13, 0xbfb8aa3b, v75
	v_exp_f32_e32 v13, v13
	s_nop 0
	v_add_f32_e32 v13, 1.0, v13
	v_div_scale_f32 v15, s[30:31], v13, v13, v75
	v_rcp_f32_e32 v17, v15
	v_div_scale_f32 v19, vcc, v75, v13, v75
	v_fma_f32 v21, -v15, v17, 1.0
	v_fmac_f32_e32 v17, v21, v17
	v_mul_f32_e32 v21, v19, v17
	v_fma_f32 v23, -v15, v21, v19
	v_fmac_f32_e32 v21, v23, v17
	v_fma_f32 v15, -v15, v21, v19
	v_div_fmas_f32 v15, v15, v17, v21
	v_div_fixup_f32 v3, v15, v13, v75
	ds_write_b32 v11, v3 offset:10240
	s_waitcnt vmcnt(11)
	v_mul_f32_e32 v13, 0xbfb8aa3b, v76
	v_exp_f32_e32 v13, v13
	s_nop 0
	v_add_f32_e32 v13, 1.0, v13
	v_div_scale_f32 v15, s[30:31], v13, v13, v76
	v_rcp_f32_e32 v17, v15
	v_div_scale_f32 v19, vcc, v76, v13, v76
	v_fma_f32 v21, -v15, v17, 1.0
	v_fmac_f32_e32 v17, v21, v17
	v_mul_f32_e32 v21, v19, v17
	v_fma_f32 v23, -v15, v21, v19
	v_fmac_f32_e32 v21, v23, v17
	v_fma_f32 v15, -v15, v21, v19
	v_div_fmas_f32 v15, v15, v17, v21
	v_div_fixup_f32 v0, v15, v13, v76
	ds_write_b32 v11, v0 offset:12288
	s_waitcnt vmcnt(10)
	v_mul_f32_e32 v13, 0xbfb8aa3b, v77
	v_exp_f32_e32 v13, v13
	s_nop 0
	v_add_f32_e32 v13, 1.0, v13
	v_div_scale_f32 v15, s[30:31], v13, v13, v77
	v_rcp_f32_e32 v17, v15
	v_div_scale_f32 v19, vcc, v77, v13, v77
	v_fma_f32 v21, -v15, v17, 1.0
	v_fmac_f32_e32 v17, v21, v17
	v_mul_f32_e32 v21, v19, v17
	v_fma_f32 v23, -v15, v21, v19
	v_fmac_f32_e32 v21, v23, v17
	v_fma_f32 v15, -v15, v21, v19
	v_div_fmas_f32 v15, v15, v17, v21
	v_div_fixup_f32 v3, v15, v13, v77
	ds_write_b32 v11, v3 offset:14336
	s_waitcnt vmcnt(9)
	v_mul_f32_e32 v13, 0xbfb8aa3b, v78
	v_exp_f32_e32 v13, v13
	s_nop 0
	v_add_f32_e32 v13, 1.0, v13
	v_div_scale_f32 v15, s[30:31], v13, v13, v78
	v_rcp_f32_e32 v17, v15
	v_div_scale_f32 v19, vcc, v78, v13, v78
	v_fma_f32 v21, -v15, v17, 1.0
	v_fmac_f32_e32 v17, v21, v17
	v_mul_f32_e32 v21, v19, v17
	v_fma_f32 v23, -v15, v21, v19
	v_fmac_f32_e32 v21, v23, v17
	v_fma_f32 v15, -v15, v21, v19
	v_div_fmas_f32 v15, v15, v17, v21
	v_div_fixup_f32 v0, v15, v13, v78
	ds_write_b32 v11, v0 offset:16384
	s_waitcnt vmcnt(8)
; __device__ __forceinline__ void p0_ada_item(LAS unsigned char* lds, const Params& P, int item) {
;     ...
;     for (int i = tid; i < 9 * 1024; i += NTHREADS) { const int r = i >> 10, k = i & 1023; const float v = r < 8 ? P.c[r * 1024 + k] : P.c_ctx[k]; S[i] = v / (1.0f + __expf(-v)); }
	v_mul_f32_e32 v13, 0xbfb8aa3b, v79
	v_exp_f32_e32 v13, v13
	s_nop 0
	v_add_f32_e32 v13, 1.0, v13
	v_div_scale_f32 v15, s[30:31], v13, v13, v79
	v_rcp_f32_e32 v17, v15
	v_div_scale_f32 v19, vcc, v79, v13, v79
	v_fma_f32 v21, -v15, v17, 1.0
	v_fmac_f32_e32 v17, v21, v17
	v_mul_f32_e32 v21, v19, v17
	v_fma_f32 v23, -v15, v21, v19
	v_fmac_f32_e32 v21, v23, v17
	v_fma_f32 v15, -v15, v21, v19
	v_div_fmas_f32 v15, v15, v17, v21
	v_div_fixup_f32 v3, v15, v13, v79
	ds_write_b32 v11, v3 offset:18432
	s_waitcnt vmcnt(7)
	v_mul_f32_e32 v13, 0xbfb8aa3b, v80
	v_exp_f32_e32 v13, v13
	s_nop 0
	v_add_f32_e32 v13, 1.0, v13
	v_div_scale_f32 v15, s[30:31], v13, v13, v80
	v_rcp_f32_e32 v17, v15
	v_div_scale_f32 v19, vcc, v80, v13, v80
	v_fma_f32 v21, -v15, v17, 1.0
	v_fmac_f32_e32 v17, v21, v17
	v_mul_f32_e32 v21, v19, v17
	v_fma_f32 v23, -v15, v21, v19
	v_fmac_f32_e32 v21, v23, v17
	v_fma_f32 v15, -v15, v21, v19
	v_div_fmas_f32 v15, v15, v17, v21
	v_div_fixup_f32 v0, v15, v13, v80
	ds_write_b32 v11, v0 offset:20480
	s_waitcnt vmcnt(6)
	v_mul_f32_e32 v13, 0xbfb8aa3b, v81
	v_exp_f32_e32 v13, v13
	s_nop 0
	v_add_f32_e32 v13, 1.0, v13
	v_div_scale_f32 v15, s[30:31], v13, v13, v81
	v_rcp_f32_e32 v17, v15
	v_div_scale_f32 v19, vcc, v81, v13, v81
	v_fma_f32 v21, -v15, v17, 1.0
	v_fmac_f32_e32 v17, v21, v17
	v_mul_f32_e32 v21, v19, v17
	v_fma_f32 v23, -v15, v21, v19
	v_fmac_f32_e32 v21, v23, v17
	v_fma_f32 v15, -v15, v21, v19
	v_div_fmas_f32 v15, v15, v17, v21
	v_div_fixup_f32 v3, v15, v13, v81
	ds_write_b32 v11, v3 offset:22528
	s_waitcnt vmcnt(5)
	v_mul_f32_e32 v13, 0xbfb8aa3b, v82
	v_exp_f32_e32 v13, v13
	s_nop 0
	v_add_f32_e32 v13, 1.0, v13
	v_div_scale_f32 v15, s[30:31], v13, v13, v82
	v_rcp_f32_e32 v17, v15
	v_div_scale_f32 v19, vcc, v82, v13, v82
	v_fma_f32 v21, -v15, v17, 1.0
	v_fmac_f32_e32 v17, v21, v17
	v_mul_f32_e32 v21, v19, v17
	v_fma_f32 v23, -v15, v21, v19
	v_fmac_f32_e32 v21, v23, v17
	v_fma_f32 v15, -v15, v21, v19
	v_div_fmas_f32 v15, v15, v17, v21
	v_div_fixup_f32 v0, v15, v13, v82
	ds_write_b32 v11, v0 offset:24576
	s_waitcnt vmcnt(4)
	v_mul_f32_e32 v13, 0xbfb8aa3b, v83
	v_exp_f32_e32 v13, v13
	s_nop 0
	v_add_f32_e32 v13, 1.0, v13
	v_div_scale_f32 v15, s[30:31], v13, v13, v83
	v_rcp_f32_e32 v17, v15
	v_div_scale_f32 v19, vcc, v83, v13, v83
	v_fma_f32 v21, -v15, v17, 1.0
	v_fmac_f32_e32 v17, v21, v17
	v_mul_f32_e32 v21, v19, v17
	v_fma_f32 v23, -v15, v21, v19
	v_fmac_f32_e32 v21, v23, v17
	v_fma_f32 v15, -v15, v21, v19
	v_div_fmas_f32 v15, v15, v17, v21
	v_div_fixup_f32 v3, v15, v13, v83
	ds_write_b32 v11, v3 offset:26624
	s_waitcnt vmcnt(3)
	v_mul_f32_e32 v13, 0xbfb8aa3b, v84
	v_exp_f32_e32 v13, v13
	s_nop 0
	v_add_f32_e32 v13, 1.0, v13
	v_div_scale_f32 v15, s[30:31], v13, v13, v84
	v_rcp_f32_e32 v17, v15
	v_div_scale_f32 v19, vcc, v84, v13, v84
	v_fma_f32 v21, -v15, v17, 1.0
	v_fmac_f32_e32 v17, v21, v17
	v_mul_f32_e32 v21, v19, v17
	v_fma_f32 v23, -v15, v21, v19
	v_fmac_f32_e32 v21, v23, v17
	v_fma_f32 v15, -v15, v21, v19
	v_div_fmas_f32 v15, v15, v17, v21
	v_div_fixup_f32 v0, v15, v13, v84
	ds_write_b32 v11, v0 offset:28672
	s_waitcnt vmcnt(2)
	v_mul_f32_e32 v13, 0xbfb8aa3b, v85
	v_exp_f32_e32 v13, v13
	s_nop 0
	v_add_f32_e32 v13, 1.0, v13
	v_div_scale_f32 v15, s[30:31], v13, v13, v85
	v_rcp_f32_e32 v17, v15
	v_div_scale_f32 v19, vcc, v85, v13, v85
	v_fma_f32 v21, -v15, v17, 1.0
	v_fmac_f32_e32 v17, v21, v17
	v_mul_f32_e32 v21, v19, v17
	v_fma_f32 v23, -v15, v21, v19
	v_fmac_f32_e32 v21, v23, v17
	v_fma_f32 v15, -v15, v21, v19
	v_div_fmas_f32 v15, v15, v17, v21
	v_div_fixup_f32 v3, v15, v13, v85
	ds_write_b32 v11, v3 offset:30720
	s_waitcnt vmcnt(1)
	v_mul_f32_e32 v13, 0xbfb8aa3b, v86
	v_exp_f32_e32 v13, v13
	s_nop 0
	v_add_f32_e32 v13, 1.0, v13
	v_div_scale_f32 v15, s[30:31], v13, v13, v86
	v_rcp_f32_e32 v17, v15
	v_div_scale_f32 v19, vcc, v86, v13, v86
	v_fma_f32 v21, -v15, v17, 1.0
	v_fmac_f32_e32 v17, v21, v17
	v_mul_f32_e32 v21, v19, v17
	v_fma_f32 v23, -v15, v21, v19
	v_fmac_f32_e32 v21, v23, v17
	v_fma_f32 v15, -v15, v21, v19
	v_div_fmas_f32 v15, v15, v17, v21
	v_div_fixup_f32 v0, v15, v13, v86
	ds_write_b32 v11, v0 offset:32768
	s_waitcnt vmcnt(0)
	v_mul_f32_e32 v13, 0xbfb8aa3b, v87
	v_exp_f32_e32 v13, v13
	s_nop 0
	v_add_f32_e32 v13, 1.0, v13
	v_div_scale_f32 v15, s[30:31], v13, v13, v87
	v_rcp_f32_e32 v17, v15
	v_div_scale_f32 v19, vcc, v87, v13, v87
	v_fma_f32 v21, -v15, v17, 1.0
	v_fmac_f32_e32 v17, v21, v17
	v_mul_f32_e32 v21, v19, v17
	v_fma_f32 v23, -v15, v21, v19
	v_fmac_f32_e32 v21, v23, v17
	v_fma_f32 v15, -v15, v21, v19
	v_div_fmas_f32 v15, v15, v17, v21
	v_div_fixup_f32 v3, v15, v13, v87
	ds_write_b32 v11, v3 offset:34816
